# one static s_setprio 1 for waves 4..7 (the wave half that runs one barrier phase behind), set once at kernel start; no per-segment toggles
# baseline (speedup 1.0000x reference)
; DEVI unsigned xb_add(unsigned* q, unsigned v) { return __hip_atomic_fetch_add(q, v, __ATOMIC_RELAXED, __HIP_MEMORY_SCOPE_AGENT); }
; DEVI unsigned xb_xcc_id() { return (unsigned)__builtin_amdgcn_s_getreg((3 << 11) | 20) & 0xFu; }
; __global__ void __launch_bounds__(NTHREADS) mega(Params p_in) {
;   cg::grid_group grid = cg::this_grid();
;   Params p = p_in;
;   p.wv = __builtin_amdgcn_readfirstlane((int)(threadIdx.x >> 6));
;   if (threadIdx.x == 0) {
;     volatile unsigned* st = (volatile unsigned*)(smem + LDS_BYTES - 256); st[0] = 0u; st[1] = 0u;
;     (void)xb_add(&((unsigned*)(p.ws + OFF_BAR))[XB_XCNT(xb_xcc_id())], 1u);
;   }
;   __syncthreads();
;   phase0(p);
.LBB0_6:
	s_load_dwordx16 s[36:51], s[0:1], 0x0
	s_load_dwordx16 s[16:31], s[0:1], 0x40
	s_andn2_b64 vcc, exec, s[4:5]
	s_waitcnt lgkmcnt(0)
	v_writelane_b32 v252, s36, 14
	s_nop 1
	v_writelane_b32 v252, s37, 15
	v_writelane_b32 v252, s38, 16
	v_writelane_b32 v252, s39, 17
	v_writelane_b32 v252, s40, 18
	v_writelane_b32 v252, s41, 19
	v_writelane_b32 v252, s42, 20
	v_writelane_b32 v252, s43, 21
	v_writelane_b32 v252, s44, 22
	v_writelane_b32 v252, s45, 23
	v_writelane_b32 v252, s46, 24
	v_writelane_b32 v252, s47, 25
	v_writelane_b32 v252, s48, 26
	v_writelane_b32 v252, s49, 27
	v_writelane_b32 v252, s50, 28
	v_writelane_b32 v252, s51, 29
	v_writelane_b32 v252, s16, 30
	s_nop 1
	v_writelane_b32 v252, s17, 31
	v_writelane_b32 v252, s18, 32
	v_writelane_b32 v252, s19, 33
	v_writelane_b32 v252, s20, 34
	v_writelane_b32 v252, s21, 35
	v_writelane_b32 v252, s22, 36
	v_writelane_b32 v252, s23, 37
	v_writelane_b32 v252, s24, 38
	v_writelane_b32 v252, s25, 39
	v_writelane_b32 v252, s26, 40
	v_writelane_b32 v252, s27, 41
	v_writelane_b32 v252, s28, 42
	v_writelane_b32 v252, s29, 43
	v_writelane_b32 v252, s30, 44
	v_writelane_b32 v252, s31, 45
	s_load_dwordx16 s[16:31], s[0:1], 0x80
	s_waitcnt lgkmcnt(0)
	v_writelane_b32 v252, s16, 46
	s_nop 1
	v_writelane_b32 v252, s17, 47
	v_writelane_b32 v252, s18, 48
	v_writelane_b32 v252, s19, 49
	v_writelane_b32 v252, s20, 50
	v_writelane_b32 v252, s21, 51
	v_writelane_b32 v252, s22, 52
	v_writelane_b32 v252, s23, 53
	v_writelane_b32 v252, s24, 54
	v_writelane_b32 v252, s25, 55
	v_writelane_b32 v252, s26, 56
	v_writelane_b32 v252, s27, 57
	v_writelane_b32 v252, s28, 58
	v_writelane_b32 v252, s29, 59
	v_writelane_b32 v252, s30, 60
	v_writelane_b32 v252, s31, 61
	s_cbranch_vccnz .LBB0_572
	s_add_u32 s2, s70, 0x1d100000
	v_readlane_b32 s0, v252, 13
	s_addc_u32 s68, s71, 0
	s_and_b32 s33, s0, 0xffffffc0
	s_add_u32 s69, s70, 0x1c900000
	s_addc_u32 s72, s71, 0
	s_add_u32 s73, s70, 0x1b300000
	s_addc_u32 s74, s71, 0
	s_add_u32 s75, s70, 0x18700000
	s_addc_u32 s54, s71, 0
	s_add_u32 s55, s70, 0x1d500000
	s_addc_u32 s56, s71, 0
	s_add_u32 s14, s70, 0x1dda2000
	s_addc_u32 s15, s71, 0
	s_add_u32 s16, s70, 0x1d9a2000
	v_readlane_b32 s36, v252, 46
	s_addc_u32 s17, s71, 0
	v_readlane_b32 s44, v252, 54
	v_readlane_b32 s45, v252, 55
	s_add_u32 s18, s44, 0x2100
	v_readlane_b32 s46, v252, 56
	s_addc_u32 s19, s45, 0
	v_readlane_b32 s47, v252, 57
	s_add_u32 s20, s46, 0x100
	v_readlane_b32 s48, v252, 58
	s_addc_u32 s21, s47, 0
	v_readlane_b32 s49, v252, 59
	s_add_u32 s22, s48, 0x8000
	v_readlane_b32 s50, v252, 60
	s_addc_u32 s23, s49, 0
	v_readlane_b32 s51, v252, 61
	s_add_u32 s24, s50, 0x200
	s_addc_u32 s25, s51, 0
	v_readlane_b32 s4, v252, 5
	v_readlane_b32 s5, v252, 6
	s_add_u32 s26, s4, 0x100
	v_readlane_b32 s6, v252, 7
	s_addc_u32 s27, s5, 0
	v_readlane_b32 s7, v252, 8
	s_add_u32 s28, s6, 0x20000
	s_addc_u32 s29, s7, 0
	s_add_u32 s34, s70, 0x1d5a2000
	s_addc_u32 s35, s71, 0
	v_mov_b32_e32 v119, 0
	s_movk_i32 s57, 0x404
	s_movk_i32 s58, 0x1600
	s_movk_i32 s59, 0x5800
	s_movk_i32 s60, 0x90
	s_mov_b32 s61, 0x9000
	v_mov_b32_e32 v123, 0x38d1b717
	v_mov_b32_e32 v148, 0xc0447cbd
	v_mov_b32_e32 v149, 0x100
	v_mov_b32_e32 v150, 0x1000
	s_add_i32 s62, 0, 0xa400
	s_add_i32 s63, 0, 0x6400
	v_readlane_b32 s64, v252, 0
	s_mov_b32 s53, 0
	v_readlane_b32 s37, v252, 47
	v_readlane_b32 s38, v252, 48
	v_readlane_b32 s39, v252, 49
	v_readlane_b32 s40, v252, 50
	v_readlane_b32 s41, v252, 51
	v_readlane_b32 s42, v252, 52
	v_readlane_b32 s43, v252, 53
	v_readlane_b32 s8, v252, 9
	v_readlane_b32 s9, v252, 10
	v_readlane_b32 s10, v252, 11
	v_readlane_b32 s11, v252, 12
	s_cmpk_lt_u32 s33, 0x100
	s_cbranch_scc1 .Lmy_sprio_skip
	s_setprio 1
.Lmy_sprio_skip:
	s_cmpk_eq_u32 s3, 0x100
	s_cbranch_scc0 .Lmy_rot_skip
	s_add_i32 s64, s64, 0x84
	s_and_b32 s64, s64, 0xff
